# longer s_sleep between grid-barrier polls
# baseline (speedup 1.0000x reference)
.LBB0_11:
	s_sleep 6
	global_load_dword v3, v2, s[6:7] offset:32 sc1
	s_waitcnt vmcnt(0)
	v_and_b32_e32 v3, 0xffff0000, v3
	v_cmp_ne_u32_e32 vcc, v3, v1
	s_or_b64 s[8:9], vcc, s[8:9]
	s_andn2_b64 exec, exec, s[8:9]
	s_cbranch_execnz .LBB0_11

.LBB0_175:
	global_load_dword v15, v16, s[10:11] sc1
	s_waitcnt lgkmcnt(0)
	global_load_dword v0, v16, s[28:29] sc1
	global_load_dword v1, v16, s[34:35] sc1
	global_load_dword v2, v16, s[58:59] sc1
	global_load_dword v3, v16, s[68:69] sc1
	global_load_dword v4, v16, s[70:71] sc1
	global_load_dword v5, v16, s[80:81] sc1
	global_load_dword v6, v16, s[84:85] sc1
	global_load_dword v7, v16, s[86:87] sc1
	global_load_dword v8, v16, s[88:89] sc1
	global_load_dword v9, v16, s[90:91] sc1
	global_load_dword v10, v16, s[92:93] sc1
	global_load_dword v11, v16, s[94:95] sc1
	global_load_dword v12, v16, s[96:97] sc1
	global_load_dword v13, v16, s[98:99] sc1
	global_load_dword v14, v16, s[60:61] sc1
	s_mov_b64 s[62:63], -1
	s_mov_b64 s[64:65], -1
	s_waitcnt vmcnt(14)
	v_add_u32_e32 v17, v0, v15
	s_waitcnt vmcnt(13)
	v_add_u32_e32 v17, v17, v1
	s_waitcnt vmcnt(12)
	v_add_u32_e32 v17, v17, v2
	s_waitcnt vmcnt(11)
	v_add_u32_e32 v17, v17, v3
	s_waitcnt vmcnt(10)
	v_add_u32_e32 v17, v17, v4
	s_waitcnt vmcnt(9)
	v_add_u32_e32 v17, v17, v5
	s_waitcnt vmcnt(8)
	v_add_u32_e32 v17, v17, v6
	s_waitcnt vmcnt(7)
	v_add_u32_e32 v17, v17, v7
	s_waitcnt vmcnt(6)
	v_add_u32_e32 v17, v17, v8
	s_waitcnt vmcnt(5)
	v_add_u32_e32 v17, v17, v9
	s_waitcnt vmcnt(4)
	v_add_u32_e32 v17, v17, v10
	s_waitcnt vmcnt(3)
	v_add_u32_e32 v17, v17, v11
	s_waitcnt vmcnt(2)
	v_add_u32_e32 v17, v17, v12
	s_waitcnt vmcnt(1)
	v_add_u32_e32 v17, v17, v13
	s_waitcnt vmcnt(0)
	v_add_u32_e32 v17, v17, v14
	v_cmp_eq_u32_e32 vcc, s3, v17
	s_cbranch_vccnz .LBB0_174
	s_and_b32 s62, s33, 0xff
	s_cmp_eq_u32 s62, 0
	s_mov_b64 s[62:63], -1
	s_mov_b64 s[66:67], -1
	s_sleep 6
	s_cbranch_scc1 .LBB0_179
	s_and_b64 vcc, exec, s[66:67]
	s_cbranch_vccz .LBB0_174

.LBB0_193:
	s_and_b32 s33, s3, 0xff
	s_mov_b64 s[64:65], -1
	s_cmp_lg_u32 s33, 0
	s_mov_b64 s[68:69], -1
	s_sleep 6
	s_cbranch_scc0 .LBB0_196
	s_and_b64 vcc, exec, s[68:69]
	s_cbranch_vccz .LBB0_192

.LBB0_210:
	s_and_b32 s33, s3, 0xff
	s_cmp_lg_u32 s33, 0
	s_mov_b64 s[68:69], -1
	s_sleep 6
	s_cbranch_scc0 .LBB0_213
	s_mov_b64 s[70:71], -1
	s_and_b64 vcc, exec, s[68:69]
	s_cbranch_vccz .LBB0_209

.LBB0_368:
	global_load_dword v15, v16, s[8:9] sc1
	s_waitcnt lgkmcnt(0)
	global_load_dword v0, v16, s[10:11] sc1
	global_load_dword v1, v16, s[20:21] sc1
	global_load_dword v2, v16, s[22:23] sc1
	global_load_dword v3, v16, s[28:29] sc1
	global_load_dword v4, v16, s[34:35] sc1
	global_load_dword v5, v16, s[38:39] sc1
	global_load_dword v6, v16, s[40:41] sc1
	global_load_dword v7, v16, s[42:43] sc1
	global_load_dword v8, v16, s[44:45] sc1
	global_load_dword v9, v16, s[46:47] sc1
	global_load_dword v10, v16, s[48:49] sc1
	global_load_dword v11, v16, s[50:51] sc1
	global_load_dword v12, v16, s[62:63] sc1
	global_load_dword v13, v16, s[66:67] sc1
	global_load_dword v14, v16, s[60:61] sc1
	s_mov_b64 s[64:65], -1
	s_mov_b64 s[68:69], -1
	s_waitcnt vmcnt(14)
	v_add_u32_e32 v17, v0, v15
	s_waitcnt vmcnt(13)
	v_add_u32_e32 v17, v17, v1
	s_waitcnt vmcnt(12)
	v_add_u32_e32 v17, v17, v2
	s_waitcnt vmcnt(11)
	v_add_u32_e32 v17, v17, v3
	s_waitcnt vmcnt(10)
	v_add_u32_e32 v17, v17, v4
	s_waitcnt vmcnt(9)
	v_add_u32_e32 v17, v17, v5
	s_waitcnt vmcnt(8)
	v_add_u32_e32 v17, v17, v6
	s_waitcnt vmcnt(7)
	v_add_u32_e32 v17, v17, v7
	s_waitcnt vmcnt(6)
	v_add_u32_e32 v17, v17, v8
	s_waitcnt vmcnt(5)
	v_add_u32_e32 v17, v17, v9
	s_waitcnt vmcnt(4)
	v_add_u32_e32 v17, v17, v10
	s_waitcnt vmcnt(3)
	v_add_u32_e32 v17, v17, v11
	s_waitcnt vmcnt(2)
	v_add_u32_e32 v17, v17, v12
	s_waitcnt vmcnt(1)
	v_add_u32_e32 v17, v17, v13
	s_waitcnt vmcnt(0)
	v_add_u32_e32 v17, v17, v14
	v_cmp_eq_u32_e32 vcc, s3, v17
	s_cbranch_vccnz .LBB0_367
	s_and_b32 s64, s33, 0xff
	s_cmp_eq_u32 s64, 0
	s_mov_b64 s[64:65], -1
	s_mov_b64 s[70:71], -1
	s_sleep 6
	s_cbranch_scc1 .LBB0_372
	s_and_b64 vcc, exec, s[70:71]
	s_cbranch_vccz .LBB0_367

.LBB0_386:
	s_and_b32 s33, s3, 0xff
	s_mov_b64 s[38:39], -1
	s_cmp_lg_u32 s33, 0
	s_mov_b64 s[42:43], -1
	s_sleep 6
	s_cbranch_scc0 .LBB0_389
	s_and_b64 vcc, exec, s[42:43]
	s_cbranch_vccz .LBB0_385

.LBB0_403:
	s_and_b32 s33, s3, 0xff
	s_cmp_lg_u32 s33, 0
	s_mov_b64 s[40:41], -1
	s_sleep 6
	s_cbranch_scc0 .LBB0_406
	s_mov_b64 s[42:43], -1
	s_and_b64 vcc, exec, s[40:41]
	s_cbranch_vccz .LBB0_402

.LBB0_474:
	global_load_dword v15, v16, s[10:11] sc1
	s_waitcnt lgkmcnt(0)
	global_load_dword v0, v16, s[16:17] sc1
	global_load_dword v1, v16, s[18:19] sc1
	global_load_dword v2, v16, s[20:21] sc1
	global_load_dword v3, v16, s[22:23] sc1
	global_load_dword v4, v16, s[24:25] sc1
	global_load_dword v5, v16, s[26:27] sc1
	global_load_dword v6, v16, s[28:29] sc1
	global_load_dword v7, v16, s[34:35] sc1
	global_load_dword v8, v16, s[36:37] sc1
	global_load_dword v9, v16, s[38:39] sc1
	global_load_dword v10, v16, s[40:41] sc1
	global_load_dword v11, v16, s[42:43] sc1
	global_load_dword v12, v16, s[44:45] sc1
	global_load_dword v13, v16, s[46:47] sc1
	global_load_dword v14, v16, s[48:49] sc1
	s_mov_b64 s[50:51], -1
	s_mov_b64 s[60:61], -1
	s_waitcnt vmcnt(14)
	v_add_u32_e32 v17, v0, v15
	s_waitcnt vmcnt(13)
	v_add_u32_e32 v17, v17, v1
	s_waitcnt vmcnt(12)
	v_add_u32_e32 v17, v17, v2
	s_waitcnt vmcnt(11)
	v_add_u32_e32 v17, v17, v3
	s_waitcnt vmcnt(10)
	v_add_u32_e32 v17, v17, v4
	s_waitcnt vmcnt(9)
	v_add_u32_e32 v17, v17, v5
	s_waitcnt vmcnt(8)
	v_add_u32_e32 v17, v17, v6
	s_waitcnt vmcnt(7)
	v_add_u32_e32 v17, v17, v7
	s_waitcnt vmcnt(6)
	v_add_u32_e32 v17, v17, v8
	s_waitcnt vmcnt(5)
	v_add_u32_e32 v17, v17, v9
	s_waitcnt vmcnt(4)
	v_add_u32_e32 v17, v17, v10
	s_waitcnt vmcnt(3)
	v_add_u32_e32 v17, v17, v11
	s_waitcnt vmcnt(2)
	v_add_u32_e32 v17, v17, v12
	s_waitcnt vmcnt(1)
	v_add_u32_e32 v17, v17, v13
	s_waitcnt vmcnt(0)
	v_add_u32_e32 v17, v17, v14
	v_cmp_eq_u32_e32 vcc, s3, v17
	s_cbranch_vccnz .LBB0_473
	s_and_b32 s50, s33, 0xff
	s_cmp_eq_u32 s50, 0
	s_mov_b64 s[50:51], -1
	s_mov_b64 s[62:63], -1
	s_sleep 6
	s_cbranch_scc1 .LBB0_478
	s_and_b64 vcc, exec, s[62:63]
	s_cbranch_vccz .LBB0_473

.LBB0_492:
	s_and_b32 s28, s3, 0xff
	s_mov_b64 s[26:27], -1
	s_cmp_lg_u32 s28, 0
	s_mov_b64 s[34:35], -1
	s_sleep 6
	s_cbranch_scc0 .LBB0_495
	s_and_b64 vcc, exec, s[34:35]
	s_cbranch_vccz .LBB0_491

.LBB0_509:
	s_and_b32 s28, s3, 0xff
	s_cmp_lg_u32 s28, 0
	s_mov_b64 s[34:35], -1
	s_sleep 6
	s_cbranch_scc0 .LBB0_512
	s_mov_b64 s[36:37], -1
	s_and_b64 vcc, exec, s[34:35]
	s_cbranch_vccz .LBB0_508

.LBB0_586:
	global_load_dword v15, v16, s[8:9] sc1
	s_waitcnt lgkmcnt(0)
	global_load_dword v0, v16, s[10:11] sc1
	global_load_dword v1, v16, s[16:17] sc1
	global_load_dword v2, v16, s[18:19] sc1
	global_load_dword v3, v16, s[20:21] sc1
	global_load_dword v4, v16, s[22:23] sc1
	global_load_dword v5, v16, s[24:25] sc1
	global_load_dword v6, v16, s[26:27] sc1
	global_load_dword v7, v16, s[28:29] sc1
	global_load_dword v8, v16, s[34:35] sc1
	global_load_dword v9, v16, s[36:37] sc1
	global_load_dword v10, v16, s[38:39] sc1
	global_load_dword v11, v16, s[40:41] sc1
	global_load_dword v12, v16, s[42:43] sc1
	global_load_dword v13, v16, s[44:45] sc1
	global_load_dword v14, v16, s[46:47] sc1
	s_mov_b64 s[48:49], -1
	s_mov_b64 s[50:51], -1
	s_waitcnt vmcnt(14)
	v_add_u32_e32 v17, v0, v15
	s_waitcnt vmcnt(13)
	v_add_u32_e32 v17, v17, v1
	s_waitcnt vmcnt(12)
	v_add_u32_e32 v17, v17, v2
	s_waitcnt vmcnt(11)
	v_add_u32_e32 v17, v17, v3
	s_waitcnt vmcnt(10)
	v_add_u32_e32 v17, v17, v4
	s_waitcnt vmcnt(9)
	v_add_u32_e32 v17, v17, v5
	s_waitcnt vmcnt(8)
	v_add_u32_e32 v17, v17, v6
	s_waitcnt vmcnt(7)
	v_add_u32_e32 v17, v17, v7
	s_waitcnt vmcnt(6)
	v_add_u32_e32 v17, v17, v8
	s_waitcnt vmcnt(5)
	v_add_u32_e32 v17, v17, v9
	s_waitcnt vmcnt(4)
	v_add_u32_e32 v17, v17, v10
	s_waitcnt vmcnt(3)
	v_add_u32_e32 v17, v17, v11
	s_waitcnt vmcnt(2)
	v_add_u32_e32 v17, v17, v12
	s_waitcnt vmcnt(1)
	v_add_u32_e32 v17, v17, v13
	s_waitcnt vmcnt(0)
	v_add_u32_e32 v17, v17, v14
	v_cmp_eq_u32_e32 vcc, s3, v17
	s_cbranch_vccnz .LBB0_585
	s_and_b32 s48, s33, 0xff
	s_cmp_eq_u32 s48, 0
	s_mov_b64 s[48:49], -1
	s_mov_b64 s[60:61], -1
	s_sleep 6
	s_cbranch_scc1 .LBB0_590
	s_and_b64 vcc, exec, s[60:61]
	s_cbranch_vccz .LBB0_585

.LBB0_604:
	s_and_b32 s26, s3, 0xff
	s_mov_b64 s[24:25], -1
	s_cmp_lg_u32 s26, 0
	s_mov_b64 s[28:29], -1
	s_sleep 6
	s_cbranch_scc0 .LBB0_607
	s_and_b64 vcc, exec, s[28:29]
	s_cbranch_vccz .LBB0_603

.LBB0_621:
	s_and_b32 s24, s3, 0xff
	s_cmp_lg_u32 s24, 0
	s_mov_b64 s[26:27], -1
	s_sleep 6
	s_cbranch_scc0 .LBB0_624
	s_mov_b64 s[28:29], -1
	s_and_b64 vcc, exec, s[26:27]
	s_cbranch_vccz .LBB0_620

.LBB0_681:
	global_load_dword v15, v16, s[8:9] sc1
	s_waitcnt lgkmcnt(0)
	global_load_dword v0, v16, s[10:11] sc1
	global_load_dword v1, v16, s[12:13] sc1
	global_load_dword v2, v16, s[16:17] sc1
	global_load_dword v3, v16, s[18:19] sc1
	global_load_dword v4, v16, s[20:21] sc1
	global_load_dword v5, v16, s[22:23] sc1
	global_load_dword v6, v16, s[24:25] sc1
	global_load_dword v7, v16, s[26:27] sc1
	global_load_dword v8, v16, s[28:29] sc1
	global_load_dword v9, v16, s[30:31] sc1
	global_load_dword v10, v16, s[34:35] sc1
	global_load_dword v11, v16, s[36:37] sc1
	global_load_dword v12, v16, s[38:39] sc1
	global_load_dword v13, v16, s[40:41] sc1
	global_load_dword v14, v16, s[42:43] sc1
	s_mov_b64 s[44:45], -1
	s_mov_b64 s[46:47], -1
	s_waitcnt vmcnt(14)
	v_add_u32_e32 v17, v0, v15
	s_waitcnt vmcnt(13)
	v_add_u32_e32 v17, v17, v1
	s_waitcnt vmcnt(12)
	v_add_u32_e32 v17, v17, v2
	s_waitcnt vmcnt(11)
	v_add_u32_e32 v17, v17, v3
	s_waitcnt vmcnt(10)
	v_add_u32_e32 v17, v17, v4
	s_waitcnt vmcnt(9)
	v_add_u32_e32 v17, v17, v5
	s_waitcnt vmcnt(8)
	v_add_u32_e32 v17, v17, v6
	s_waitcnt vmcnt(7)
	v_add_u32_e32 v17, v17, v7
	s_waitcnt vmcnt(6)
	v_add_u32_e32 v17, v17, v8
	s_waitcnt vmcnt(5)
	v_add_u32_e32 v17, v17, v9
	s_waitcnt vmcnt(4)
	v_add_u32_e32 v17, v17, v10
	s_waitcnt vmcnt(3)
	v_add_u32_e32 v17, v17, v11
	s_waitcnt vmcnt(2)
	v_add_u32_e32 v17, v17, v12
	s_waitcnt vmcnt(1)
	v_add_u32_e32 v17, v17, v13
	s_waitcnt vmcnt(0)
	v_add_u32_e32 v17, v17, v14
	v_cmp_eq_u32_e32 vcc, s3, v17
	s_cbranch_vccnz .LBB0_680
	s_and_b32 s44, s33, 0xff
	s_cmp_eq_u32 s44, 0
	s_mov_b64 s[44:45], -1
	s_mov_b64 s[48:49], -1
	s_sleep 6
	s_cbranch_scc1 .LBB0_685
	s_and_b64 vcc, exec, s[48:49]
	s_cbranch_vccz .LBB0_680

.LBB0_699:
	s_and_b32 s24, s3, 0xff
	s_mov_b64 s[22:23], -1
	s_cmp_lg_u32 s24, 0
	s_mov_b64 s[26:27], -1
	s_sleep 6
	s_cbranch_scc0 .LBB0_702
	s_and_b64 vcc, exec, s[26:27]
	s_cbranch_vccz .LBB0_698

.LBB0_716:
	s_and_b32 s22, s3, 0xff
	s_cmp_lg_u32 s22, 0
	s_mov_b64 s[24:25], -1
	s_sleep 6
	s_cbranch_scc0 .LBB0_719
	s_mov_b64 s[26:27], -1
	s_and_b64 vcc, exec, s[24:25]
	s_cbranch_vccz .LBB0_715
